# static s_setprio 1 for workgroups 352..511 (second workgroup on CUs without an HGRN workgroup)
# speedup vs baseline: 1.0036x; 1.0036x over previous
; DI void phase0(const Params& p, char* smem) {
;   const int nb = gridDim.x, b = blockIdx.x;
;   for (int u = b; u < 2688; u += nb) transpose_unit(p, u, smem);
; __global__ void __launch_bounds__(256, 2) hymba_mega(Params p0) {
;   __shared__ __attribute__((aligned(16))) char smem[SMEM_BYTES];
;   Params p = p0;
;   p.wid = __builtin_amdgcn_readfirstlane(threadIdx.x >> 6);
;   const unsigned nb = gridDim.x;
;   run_phase<0>(p, smem); cg::this_grid().sync();
_Z10hymba_mega6Params:
	s_cmp_lt_u32 s2, 0x160
	s_cbranch_scc1 .Lprio_skip
	s_setprio 1
.Lprio_skip:
	s_load_dwordx16 s[44:59], s[0:1], 0x0
	s_load_dwordx8 s[88:95], s[0:1], 0x40
	v_and_b32_e32 v18, 0x3ff, v0
	s_load_dwordx4 s[68:71], s[0:1], 0x60
	s_load_dword s4, s[0:1], 0x78
	v_readfirstlane_b32 s33, v18
	s_andn2_b32 s33, s33, 63
	s_add_u32 s96, s0, 0x78
	s_addc_u32 s97, s1, 0
	v_mbcnt_lo_u32_b32 v1, -1, 0
	s_waitcnt lgkmcnt(0)
	v_writelane_b32 v249, s4, 0
	s_cmpk_gt_i32 s2, 0xa7f
	s_mov_b32 s5, 0
	v_mbcnt_hi_u32_b32 v234, -1, v1
	v_writelane_b32 v249, s2, 1
	s_cbranch_scc1 .LBB0_16
	s_add_u32 s18, s70, 0x1a900000
	s_addc_u32 s19, s71, 0
	s_add_u32 s20, s70, 0x19800000
	s_addc_u32 s21, s71, 0
	v_mov_b32_e32 v11, 0
	s_movk_i32 s22, 0x90
	v_readlane_b32 s23, v249, 1
	s_branch .LBB0_3
